# flat grid barrier + the last XCD leader proceeds on its atomic's returned count (no poll)
# speedup vs baseline: 1.0135x; 1.0058x over previous
.LBB0_263:
	s_waitcnt vmcnt(0)
	s_waitcnt vmcnt(0) lgkmcnt(0)
	s_barrier
	s_getreg_b32 s0, hwreg(HW_REG_HW_ID, 0, 6)
	s_and_b32 s0, s0, 63
	s_lshl_b32 s0, s0, 2
	s_add_i32 s0, s0, 0
	s_add_i32 s0, s0, 0x20400
	v_mov_b32_e32 v0, s0
	ds_read_b32 v0, v0
	s_waitcnt lgkmcnt(0)
	v_readfirstlane_b32 s0, v0
	v_mbcnt_lo_u32_b32 v0, -1, 0
	v_mbcnt_hi_u32_b32 v0, -1, v0
	s_lshl_b32 s0, s0, 6
	v_sub_u32_e32 v0, 0, v0
	v_cmp_eq_u32_e32 vcc, s0, v0
	s_and_saveexec_b64 s[2:3], vcc
	s_cbranch_execz .LBB0_315
	v_readlane_b32 s0, v255, 16
	s_waitcnt vmcnt(0) expcnt(0) lgkmcnt(0)
	v_mov_b32_e32 v7, 0
	v_mov_b32_e32 v0, s0
	ds_read_b32 v3, v0
	v_readlane_b32 s0, v255, 17
	v_mov_b32_e32 v4, 1
	v_readlane_b32 s4, v255, 7
	v_readlane_b32 s5, v255, 8
	v_mov_b32_e32 v0, s0
	ds_read_b32 v2, v0
	s_nop 2
	global_atomic_add v4, v7, v4, s[4:5] sc0
	v_readlane_b32 s4, v255, 11
	v_readlane_b32 s5, v255, 12
	s_waitcnt lgkmcnt(0)
	v_cvt_f32_u32_e32 v5, v3
	v_sub_u32_e32 v6, 0, v3
	v_rcp_iflag_f32_e32 v5, v5
	s_nop 0
	v_mul_f32_e32 v5, 0x4f7ffffe, v5
	v_cvt_u32_f32_e32 v5, v5
	v_mul_lo_u32 v0, v6, v5
	v_mul_hi_u32 v0, v5, v0
	v_add_u32_e32 v0, v5, v0
	s_waitcnt vmcnt(0)
	v_mul_hi_u32 v0, v4, v0
	v_mul_lo_u32 v6, v0, v3
	v_sub_u32_e32 v6, v4, v6
	v_cmp_ge_u32_e32 vcc, v6, v3
	v_add_u32_e32 v5, 1, v0
	s_nop 0
	v_cndmask_b32_e32 v0, v0, v5, vcc
	v_sub_u32_e32 v5, v6, v3
	v_cndmask_b32_e32 v6, v6, v5, vcc
	v_cmp_ge_u32_e32 vcc, v6, v3
	v_add_u32_e32 v5, 1, v0
	s_nop 0
	v_cndmask_b32_e32 v0, v0, v5, vcc
	v_add_u32_e32 v5, 1, v0
	v_mul_lo_u32 v6, v5, v3
	v_mul_lo_u32 v5, v5, v2
	v_add_u32_e32 v4, 1, v4
	v_cmp_eq_u32_e32 vcc, v4, v6
	s_cbranch_vccz .Lbarf_poll0
	buffer_wbl2 sc1
	v_mov_b32_e32 v4, 1
	s_waitcnt vmcnt(0)
	global_atomic_add v4, v7, v4, s[4:5] sc0
	s_waitcnt vmcnt(0)
	v_add_u32_e32 v4, 1, v4
	v_cmp_ge_u32_e32 vcc, v4, v5
	s_cbranch_vccnz .Lbarf_done0

.Lma_seam:
	s_waitcnt vmcnt(0)
	s_barrier
	s_getreg_b32 s0, hwreg(HW_REG_HW_ID, 0, 6)
	s_and_b32 s0, s0, 63
	s_lshl_b32 s0, s0, 2
	s_add_i32 s0, s0, 0
	s_add_i32 s0, s0, 0x20400
	v_mov_b32_e32 v0, s0
	ds_read_b32 v0, v0
	s_waitcnt lgkmcnt(0)
	v_readfirstlane_b32 s0, v0
	v_mbcnt_lo_u32_b32 v0, -1, 0
	v_mbcnt_hi_u32_b32 v0, -1, v0
	s_lshl_b32 s0, s0, 6
	v_sub_u32_e32 v0, 0, v0
	v_cmp_eq_u32_e32 vcc, s0, v0
	s_and_saveexec_b64 s[2:3], vcc
	s_cbranch_execz .LBB0_542
	v_readlane_b32 s0, v255, 16
	s_waitcnt vmcnt(0) expcnt(0) lgkmcnt(0)
	v_mov_b32_e32 v7, 0
	v_mov_b32_e32 v0, s0
	ds_read_b32 v3, v0
	v_readlane_b32 s0, v255, 17
	v_mov_b32_e32 v4, 1
	v_readlane_b32 s4, v255, 7
	v_readlane_b32 s5, v255, 8
	v_mov_b32_e32 v0, s0
	ds_read_b32 v2, v0
	s_nop 2
	global_atomic_add v4, v7, v4, s[4:5] sc0
	v_readlane_b32 s4, v255, 11
	v_readlane_b32 s5, v255, 12
	s_waitcnt lgkmcnt(0)
	v_cvt_f32_u32_e32 v5, v3
	v_sub_u32_e32 v6, 0, v3
	v_rcp_iflag_f32_e32 v5, v5
	s_nop 0
	v_mul_f32_e32 v5, 0x4f7ffffe, v5
	v_cvt_u32_f32_e32 v5, v5
	v_mul_lo_u32 v0, v6, v5
	v_mul_hi_u32 v0, v5, v0
	v_add_u32_e32 v0, v5, v0
	s_waitcnt vmcnt(0)
	v_mul_hi_u32 v0, v4, v0
	v_mul_lo_u32 v6, v0, v3
	v_sub_u32_e32 v6, v4, v6
	v_cmp_ge_u32_e32 vcc, v6, v3
	v_add_u32_e32 v5, 1, v0
	s_nop 0
	v_cndmask_b32_e32 v0, v0, v5, vcc
	v_sub_u32_e32 v5, v6, v3
	v_cndmask_b32_e32 v6, v6, v5, vcc
	v_cmp_ge_u32_e32 vcc, v6, v3
	v_add_u32_e32 v5, 1, v0
	s_nop 0
	v_cndmask_b32_e32 v0, v0, v5, vcc
	v_add_u32_e32 v5, 1, v0
	v_mul_lo_u32 v6, v5, v3
	v_mul_lo_u32 v5, v5, v2
	v_add_u32_e32 v4, 1, v4
	v_cmp_eq_u32_e32 vcc, v4, v6
	s_cbranch_vccz .Lbarf_poll1
	buffer_wbl2 sc1
	v_mov_b32_e32 v4, 1
	s_waitcnt vmcnt(0)
	global_atomic_add v4, v7, v4, s[4:5] sc0
	s_waitcnt vmcnt(0)
	v_add_u32_e32 v4, 1, v4
	v_cmp_ge_u32_e32 vcc, v4, v5
	s_cbranch_vccnz .Lbarf_done1

.LBB0_1650:
	v_readlane_b32 s0, v255, 16
	s_waitcnt vmcnt(0) expcnt(0) lgkmcnt(0)
	v_mov_b32_e32 v7, 0
	v_mov_b32_e32 v0, s0
	ds_read_b32 v3, v0
	v_readlane_b32 s0, v255, 17
	v_mov_b32_e32 v4, 1
	v_readlane_b32 s4, v255, 7
	v_readlane_b32 s5, v255, 8
	v_mov_b32_e32 v0, s0
	ds_read_b32 v2, v0
	s_nop 2
	global_atomic_add v4, v7, v4, s[4:5] sc0
	v_readlane_b32 s4, v255, 11
	v_readlane_b32 s5, v255, 12
	s_waitcnt lgkmcnt(0)
	v_cvt_f32_u32_e32 v5, v3
	v_sub_u32_e32 v6, 0, v3
	v_rcp_iflag_f32_e32 v5, v5
	s_nop 0
	v_mul_f32_e32 v5, 0x4f7ffffe, v5
	v_cvt_u32_f32_e32 v5, v5
	v_mul_lo_u32 v0, v6, v5
	v_mul_hi_u32 v0, v5, v0
	v_add_u32_e32 v0, v5, v0
	s_waitcnt vmcnt(0)
	v_mul_hi_u32 v0, v4, v0
	v_mul_lo_u32 v6, v0, v3
	v_sub_u32_e32 v6, v4, v6
	v_cmp_ge_u32_e32 vcc, v6, v3
	v_add_u32_e32 v5, 1, v0
	s_nop 0
	v_cndmask_b32_e32 v0, v0, v5, vcc
	v_sub_u32_e32 v5, v6, v3
	v_cndmask_b32_e32 v6, v6, v5, vcc
	v_cmp_ge_u32_e32 vcc, v6, v3
	v_add_u32_e32 v5, 1, v0
	s_nop 0
	v_cndmask_b32_e32 v0, v0, v5, vcc
	v_add_u32_e32 v5, 1, v0
	v_mul_lo_u32 v6, v5, v3
	v_mul_lo_u32 v5, v5, v2
	v_add_u32_e32 v4, 1, v4
	v_cmp_eq_u32_e32 vcc, v4, v6
	s_cbranch_vccz .Lbarf_poll7
	buffer_wbl2 sc1
	v_mov_b32_e32 v4, 1
	s_waitcnt vmcnt(0)
	global_atomic_add v4, v7, v4, s[4:5] sc0
	s_waitcnt vmcnt(0)
	v_add_u32_e32 v4, 1, v4
	v_cmp_ge_u32_e32 vcc, v4, v5
	s_cbranch_vccnz .Lbarf_done7
